# grid barrier: followers poll the top-level generation word directly, per-XCD generation word dropped
# speedup vs baseline: 1.0063x; 1.0063x over previous
.LBB0_22:
	s_or_b64 exec, exec, s[8:9]
	v_readlane_b32 s8, v240, 47
	v_readlane_b32 s9, v240, 48
	s_lshl_b64 s[8:9], s[8:9], 2
	s_add_u32 s6, s6, s8
	s_addc_u32 s7, s7, s9
	v_mov_b64_e32 v[0:1], s[6:7]
	s_waitcnt vmcnt(0) lgkmcnt(0)
	buffer_inv sc1
	s_waitcnt vmcnt(0)

.LBB0_691:
	v_readlane_b32 s8, v239, 18
	v_readlane_b32 s9, v239, 19
	s_add_u32 s8, s6, s8
	s_addc_u32 s9, s7, s9
	v_mov_b64_e32 v[4:5], s[8:9]
	flat_atomic_add v3, v[4:5], v185 sc0
	v_cvt_f32_u32_e32 v1, v2
	v_sub_u32_e32 v4, 0, v2
	v_rcp_iflag_f32_e32 v1, v1
	s_nop 0
	v_mul_f32_e32 v1, 0x4f7ffffe, v1
	v_cvt_u32_f32_e32 v1, v1
	v_mul_lo_u32 v4, v4, v1
	v_mul_hi_u32 v4, v1, v4
	v_add_u32_e32 v1, v1, v4
	s_waitcnt vmcnt(0) lgkmcnt(0)
	v_mul_hi_u32 v1, v3, v1
	v_mul_lo_u32 v4, v1, v2
	v_sub_u32_e32 v4, v3, v4
	v_cmp_ge_u32_e32 vcc, v4, v2
	v_add_u32_e32 v5, 1, v1
	s_nop 0
	v_cndmask_b32_e32 v1, v1, v5, vcc
	v_sub_u32_e32 v5, v4, v2
	v_cndmask_b32_e32 v4, v4, v5, vcc
	v_cmp_ge_u32_e32 vcc, v4, v2
	v_add_u32_e32 v4, 1, v1
	s_nop 0
	v_cndmask_b32_e32 v1, v1, v4, vcc
	v_add_u32_e32 v4, 1, v3
	v_mad_u64_u32 v[2:3], s[8:9], v2, v1, v[2:3]
	v_cmp_ne_u32_e32 vcc, v4, v2
	s_and_saveexec_b64 s[8:9], vcc
	s_xor_b64 s[8:9], exec, s[8:9]
	s_cbranch_execz .LBB0_704
	s_add_u32 s12, s6, 0x3500
	s_addc_u32 s13, s7, 0
	v_mov_b64_e32 v[2:3], s[12:13]
	flat_load_dword v0, v[2:3] sc1
	s_waitcnt vmcnt(0) lgkmcnt(0)
	v_cmp_eq_u32_e32 vcc, v0, v1
	s_and_saveexec_b64 s[10:11], vcc
	s_cbranch_execz .LBB0_703
	s_mov_b32 s28, 1
	s_mov_b64 s[14:15], 0
	s_branch .LBB0_695
